# GLA recurrence: tail over-read loads/DMAs beyond the last chunk masked off (exec=0), counts kept
# speedup vs baseline: 1.0062x; 1.0062x over previous
; __device__ __forceinline__ void gla_item(LAS unsigned char* lds, int item, const bf16_t* KDT, const float* DEC, const bf16_t* GVT, const bf16_t* GQF, bf16_t* OG) {
;     const int tid = threadIdx.x, wid = __builtin_amdgcn_readfirstlane(tid >> 6), lane = tid & 63, fr = lane & 15, fq = lane >> 4;
;     const int vs = item & 7, h = (item >> 3) & 3, b = item >> 5;
;     const bf16_t* kdt = KDT + (size_t)((b * 4 + h) * 32) * 8192 + (size_t)(wid * 2 * 64 + lane) * 8;
;     const float* dec = DEC + (size_t)((b * 4 + h) * 32) * 128 + 16 * wid + 4 * fq;
;     const bf16_t* gvt = GVT + (size_t)item * (32 * 4 * 512) + (size_t)lane * 8;
;     const int f0 = 16 * (wid & 3), v0 = 16 * (wid >> 2);
;     const bf16_t* gq = GQF + ((size_t)((b * 4 + h) * 32) * 16 + (size_t)(wid & 3) * 4) * 512 + (size_t)lane * 8;
;     bf16_t* outp = OG + (size_t)item * (SEQ * 32) + (size_t)(f0 + fr) * 32 + v0 + 4 * fq;
;     f32x4 S[2]; S[0] = (f32x4){0.f, 0.f, 0.f, 0.f}; S[1] = S[0];
;     ...
;     GlaSet s0, s1, s2;
;     GLA_LOAD(s0, 0); GLA_LOAD(s1, 1);
; #pragma unroll 1
;     for (int c = 0; c < 30; c += 3) {
;         GLA_LOAD(s2, c + 2); GLA_STEP(s0, c);
;         GLA_LOAD(s0, c + 3); GLA_STEP(s1, c + 1);
;         GLA_LOAD(s1, c + 4); GLA_STEP(s2, c + 2);
;     }
.LBB0_982:
	v_readfirstlane_b32 s53, v185
	v_lshlrev_b32_e32 v0, 4, v184
	v_lshrrev_b32_e32 v6, 4, v184
	v_and_b32_e32 v7, 15, v184
	s_lshr_b32 s53, s53, 6
	v_lshlrev_b32_e32 v1, 4, v6
	s_and_b32 s0, s52, 7
	s_lshl_b32 s0, s0, 2
	s_lshr_b32 s55, s52, 6
	s_add_i32 s0, s0, s55
	s_bfe_u32 s55, s52, 0x30003
	s_lshl_b32 s69, s0, 3
	s_add_i32 s69, s69, s55
	s_lshl_b32 s36, s0, 19
	s_lshl_b32 s37, s53, 11
	s_add_i32 s36, s36, s37
	s_add_u32 s58, s86, 0x14000000
	s_addc_u32 s59, s87, 0
	s_add_u32 s58, s58, s36
	s_addc_u32 s59, s59, 0
	s_lshl_b32 s36, s0, 14
	s_lshl_b32 s37, s53, 6
	s_add_i32 s36, s36, s37
	s_add_u32 s60, s86, 0x15000000
	s_addc_u32 s61, s87, 0
	s_add_u32 s60, s60, s36
	s_addc_u32 s61, s61, 0
	s_lshl_b32 s36, s69, 17
	s_add_u32 s62, s86, 0x10800000
	s_addc_u32 s63, s87, 0
	s_add_u32 s62, s62, s36
	s_addc_u32 s63, s63, 0
	s_add_u32 s66, s86, 0x1e000000
	s_addc_u32 s67, s87, 0
	s_add_u32 s66, s66, s36
	s_addc_u32 s67, s67, 0
	s_and_b32 s36, s53, 3
	s_lshl_b32 s36, s36, 12
	s_lshr_b32 s37, s53, 2
	s_lshl_b32 s37, s37, 11
	s_add_i32 s55, s36, s37
	s_lshl_b32 s37, s0, 19
	s_add_u32 s64, s86, 0x6800000
	s_addc_u32 s65, s87, 0
	s_add_u32 s64, s64, s37
	s_addc_u32 s65, s65, 0
	s_add_u32 s64, s64, s55
	s_addc_u32 s65, s65, 0
	s_add_i32 s36, s36, 0x1000
	v_add_u32_e32 v108, s36, v0
	s_and_b32 s36, s53, 3
	s_lshl_b32 s36, s36, 4
	v_add_u32_e32 v2, s36, v7
	v_lshlrev_b32_e32 v2, 5, v2
	s_lshr_b32 s37, s53, 2
	s_lshl_b32 s37, s37, 4
	v_lshl_add_u32 v2, v6, 2, v2
	v_add_u32_e32 v2, s37, v2
	v_lshlrev_b32_e32 v2, 1, v2
	v_mul_u32_u24_e32 v3, 0x110, v7
	s_lshl_b32 s36, s53, 5
	v_lshl_add_u32 v3, v6, 3, v3
	v_add_u32_e32 v3, s36, v3
	v_add_u32_e32 v4, s37, v7
	v_mul_u32_u24_e32 v4, 0x110, v4
	v_lshl_add_u32 v4, v6, 4, v4
	s_lshr_b32 s36, s53, 1
	s_lshl_b32 s36, s36, 10
	v_add_u32_e32 v109, s36, v0
	s_and_b32 s37, s53, 1
	s_add_i32 s53, s55, 0x1000
	s_mov_b32 s55, s36
	s_cmp_lg_u32 s37, 0
	s_cselect_b32 s36, 0, -1
	s_cselect_b32 s37, -1, 0
	s_mov_b64 s[72:73], -1
	s_mov_b64 s[74:75], -1
	s_mov_b32 s0, 0x5000
	s_and_b64 exec, s[36:37], s[72:73]
	s_add_i32 m0, s0, s55
	s_nop 0
	global_load_lds_dwordx4 v109, s[62:63]
	s_mov_b64 exec, s[72:73]
	s_add_i32 m0, s0, s53
	s_nop 0
	global_load_lds_dwordx4 v0, s[64:65]
	global_load_lds_dwordx4 v0, s[64:65] offset:1024
	s_mov_b64 exec, -1
	s_add_u32 s62, s62, 0x1000
	s_addc_u32 s63, s63, 0
	s_add_u32 s64, s64, 0x4000
	s_addc_u32 s65, s65, 0
	s_mov_b32 s0, 0xa000
	s_and_b64 exec, s[36:37], s[72:73]
	s_add_i32 m0, s0, s55
	s_nop 0
	global_load_lds_dwordx4 v109, s[62:63]
	s_mov_b64 exec, s[72:73]
	s_add_i32 m0, s0, s53
	s_nop 0
	global_load_lds_dwordx4 v0, s[64:65]
	global_load_lds_dwordx4 v0, s[64:65] offset:1024
	s_mov_b64 exec, -1
	s_add_u32 s62, s62, 0x1000
	s_addc_u32 s63, s63, 0
	s_add_u32 s64, s64, 0x4000
	s_addc_u32 s65, s65, 0
	s_mov_b32 s0, 0xf000
	s_and_b64 exec, s[36:37], s[72:73]
	s_add_i32 m0, s0, s55
	s_nop 0
	global_load_lds_dwordx4 v109, s[62:63]
	s_mov_b64 exec, s[72:73]
	s_add_i32 m0, s0, s53
	s_nop 0
	global_load_lds_dwordx4 v0, s[64:65]
	global_load_lds_dwordx4 v0, s[64:65] offset:1024
	s_mov_b64 exec, -1
	s_add_u32 s62, s62, 0x1000
	s_addc_u32 s63, s63, 0
	s_add_u32 s64, s64, 0x4000
	s_addc_u32 s65, s65, 0
	global_load_dwordx4 v[16:19], v0, s[58:59]
	global_load_dwordx4 v[20:23], v0, s[58:59] offset:1024
	global_load_dwordx4 v[24:27], v1, s[60:61]
	s_add_u32 s58, s58, 0x4000
	s_addc_u32 s59, s59, 0
	s_add_u32 s60, s60, 0x200
	s_addc_u32 s61, s61, 0
	global_load_dwordx4 v[28:31], v0, s[58:59]
	global_load_dwordx4 v[32:35], v0, s[58:59] offset:1024
	global_load_dwordx4 v[36:39], v1, s[60:61]
	s_add_u32 s58, s58, 0x4000
	s_addc_u32 s59, s59, 0
	s_add_u32 s60, s60, 0x200
	s_addc_u32 s61, s61, 0
	v_mov_b32_e32 v8, 0
	v_mov_b32_e32 v9, 0
	v_mov_b32_e32 v10, 0
	v_mov_b32_e32 v11, 0
	v_mov_b32_e32 v12, 0
	v_mov_b32_e32 v13, 0
	v_mov_b32_e32 v14, 0
	v_mov_b32_e32 v15, 0
	s_mov_b32 s54, 0
	s_mov_b32 s68, 0x5000
	s_waitcnt vmcnt(0)
	s_barrier
.Lgla_loop:
	s_waitcnt vmcnt(11)
	s_cmpk_lt_u32 s54, 0x1d
	s_cselect_b64 s[72:73], -1, 0
	s_cmpk_lt_u32 s54, 0x1e
	s_cselect_b64 s[74:75], -1, 0
	v_add_u32_e32 v5, s68, v0
	ds_read_b128 v[52:55], v5
	ds_read_b128 v[56:59], v5 offset:1024
	ds_read_b128 v[60:63], v5 offset:2048
	ds_read_b128 v[64:67], v5 offset:3072
	v_pk_mul_f32 v[8:9], v[8:9], v[24:25]
	v_pk_mul_f32 v[10:11], v[10:11], v[26:27]
	v_pk_mul_f32 v[12:13], v[12:13], v[24:25]
	v_pk_mul_f32 v[14:15], v[14:15], v[26:27]
	s_and_b32 s69, s54, 1
	s_mulk_i32 s69, 0x2200
	v_add_u32_e32 v6, s69, v3
	v_add_u32_e32 v7, s69, v4
	s_waitcnt lgkmcnt(0)
	s_nop 0
	v_mfma_f32_16x16x32_bf16 v[8:11], v[16:19], v[52:55], v[8:11]
	v_mfma_f32_16x16x32_bf16 v[12:15], v[16:19], v[60:63], v[12:15]
	v_mfma_f32_16x16x32_bf16 v[8:11], v[20:23], v[56:59], v[8:11]
	v_mfma_f32_16x16x32_bf16 v[12:15], v[20:23], v[64:67], v[12:15]
	s_mov_b64 exec, s[74:75]
	global_load_dwordx4 v[40:43], v0, s[58:59]
	global_load_dwordx4 v[44:47], v0, s[58:59] offset:1024
	global_load_dwordx4 v[48:51], v1, s[60:61]
	s_add_u32 s58, s58, 0x4000
	s_addc_u32 s59, s59, 0
	s_add_u32 s60, s60, 0x200
	s_addc_u32 s61, s61, 0
	s_mov_b64 exec, -1
	s_nop 7
	v_cvt_pk_bf16_f32 v104, v8, v9
	v_cvt_pk_bf16_f32 v105, v10, v11
	v_cvt_pk_bf16_f32 v106, v12, v13
	v_cvt_pk_bf16_f32 v107, v14, v15
	ds_write_b64 v6, v[104:105]
	ds_write_b64 v6, v[106:107] offset:4352
	s_waitcnt vmcnt(11)
	s_waitcnt lgkmcnt(0)
	s_barrier
	v_add_u32_e32 v5, s68, v108
	ds_read_b128 v[68:71], v7
	ds_read_b128 v[72:75], v7 offset:64
	ds_read_b128 v[76:79], v7 offset:128
	ds_read_b128 v[80:83], v7 offset:192
	ds_read_b128 v[84:87], v5
	ds_read_b128 v[88:91], v5 offset:1024
	ds_read_b128 v[92:95], v5 offset:2048
	ds_read_b128 v[96:99], v5 offset:3072
	s_add_i32 s0, s68, 0xffffb000
	s_cmp_lg_u32 s68, 0x5000
	s_cselect_b32 s0, s0, 0x14000
	s_and_b64 exec, s[36:37], s[72:73]
	s_add_i32 m0, s0, s55
	s_nop 0
	global_load_lds_dwordx4 v109, s[62:63]
	s_mov_b64 exec, s[72:73]
	s_add_i32 m0, s0, s53
	s_nop 0
	global_load_lds_dwordx4 v0, s[64:65]
	global_load_lds_dwordx4 v0, s[64:65] offset:1024
	s_mov_b64 exec, -1
	s_add_u32 s62, s62, 0x1000
	s_addc_u32 s63, s63, 0
	s_add_u32 s64, s64, 0x4000
	s_addc_u32 s65, s65, 0
	s_waitcnt lgkmcnt(0)
	v_mfma_f32_16x16x32_bf16 v[100:103], v[68:71], v[84:87], 0
	v_mfma_f32_16x16x32_bf16 v[100:103], v[72:75], v[88:91], v[100:103]
	v_mfma_f32_16x16x32_bf16 v[100:103], v[76:79], v[92:95], v[100:103]
	v_mfma_f32_16x16x32_bf16 v[100:103], v[80:83], v[96:99], v[100:103]
	s_add_i32 s68, s68, 0x5000
	s_cmp_lg_u32 s68, 0x19000
	s_cselect_b32 s68, s68, 0x5000
	s_nop 7
	v_pk_mul_f32 v[100:101], v[100:101], s[22:23] op_sel_hi:[1,0]
	v_pk_mul_f32 v[102:103], v[102:103], s[22:23] op_sel_hi:[1,0]
	s_cmpk_lt_u32 s54, 0x20
	v_cvt_pk_bf16_f32 v104, v100, v101
	v_cvt_pk_bf16_f32 v105, v102, v103
	s_cbranch_scc0 .Lgla_nost0
	global_store_dwordx2 v2, v[104:105], s[66:67]
; __device__ __forceinline__ void gla_item(LAS unsigned char* lds, int item, const bf16_t* KDT, const float* DEC, const bf16_t* GVT, const bf16_t* GQF, bf16_t* OG) {
;     ...
;     for (int c = 0; c < 30; c += 3) {
;         GLA_LOAD(s2, c + 2); GLA_STEP(s0, c);
;         GLA_LOAD(s0, c + 3); GLA_STEP(s1, c + 1);
;         GLA_LOAD(s1, c + 4); GLA_STEP(s2, c + 2);
;     }
.Lgla_nost0:
	s_add_u32 s66, s66, 0x1000
	s_addc_u32 s67, s67, 0
	s_add_i32 s54, s54, 1
	s_waitcnt vmcnt(11)
	s_cmpk_lt_u32 s54, 0x1d
	s_cselect_b64 s[72:73], -1, 0
	s_cmpk_lt_u32 s54, 0x1e
	s_cselect_b64 s[74:75], -1, 0
	v_add_u32_e32 v5, s68, v0
	ds_read_b128 v[52:55], v5
	ds_read_b128 v[56:59], v5 offset:1024
	ds_read_b128 v[60:63], v5 offset:2048
	ds_read_b128 v[64:67], v5 offset:3072
	v_pk_mul_f32 v[8:9], v[8:9], v[36:37]
	v_pk_mul_f32 v[10:11], v[10:11], v[38:39]
	v_pk_mul_f32 v[12:13], v[12:13], v[36:37]
	v_pk_mul_f32 v[14:15], v[14:15], v[38:39]
	s_and_b32 s69, s54, 1
	s_mulk_i32 s69, 0x2200
	v_add_u32_e32 v6, s69, v3
	v_add_u32_e32 v7, s69, v4
	s_waitcnt lgkmcnt(0)
	s_nop 0
	v_mfma_f32_16x16x32_bf16 v[8:11], v[28:31], v[52:55], v[8:11]
	v_mfma_f32_16x16x32_bf16 v[12:15], v[28:31], v[60:63], v[12:15]
	v_mfma_f32_16x16x32_bf16 v[8:11], v[32:35], v[56:59], v[8:11]
	v_mfma_f32_16x16x32_bf16 v[12:15], v[32:35], v[64:67], v[12:15]
	s_mov_b64 exec, s[74:75]
	global_load_dwordx4 v[16:19], v0, s[58:59]
	global_load_dwordx4 v[20:23], v0, s[58:59] offset:1024
	global_load_dwordx4 v[24:27], v1, s[60:61]
	s_add_u32 s58, s58, 0x4000
	s_addc_u32 s59, s59, 0
	s_add_u32 s60, s60, 0x200
	s_addc_u32 s61, s61, 0
	s_mov_b64 exec, -1
	s_nop 7
	v_cvt_pk_bf16_f32 v104, v8, v9
	v_cvt_pk_bf16_f32 v105, v10, v11
	v_cvt_pk_bf16_f32 v106, v12, v13
	v_cvt_pk_bf16_f32 v107, v14, v15
	ds_write_b64 v6, v[104:105]
	ds_write_b64 v6, v[106:107] offset:4352
	s_waitcnt vmcnt(11)
	s_waitcnt lgkmcnt(0)
	s_barrier
	v_add_u32_e32 v5, s68, v108
	ds_read_b128 v[68:71], v7
	ds_read_b128 v[72:75], v7 offset:64
	ds_read_b128 v[76:79], v7 offset:128
	ds_read_b128 v[80:83], v7 offset:192
	ds_read_b128 v[84:87], v5
	ds_read_b128 v[88:91], v5 offset:1024
	ds_read_b128 v[92:95], v5 offset:2048
	ds_read_b128 v[96:99], v5 offset:3072
	s_add_i32 s0, s68, 0xffffb000
	s_cmp_lg_u32 s68, 0x5000
	s_cselect_b32 s0, s0, 0x14000
	s_and_b64 exec, s[36:37], s[72:73]
	s_add_i32 m0, s0, s55
	s_nop 0
	global_load_lds_dwordx4 v109, s[62:63]
	s_mov_b64 exec, s[72:73]
	s_add_i32 m0, s0, s53
	s_nop 0
	global_load_lds_dwordx4 v0, s[64:65]
	global_load_lds_dwordx4 v0, s[64:65] offset:1024
	s_mov_b64 exec, -1
	s_add_u32 s62, s62, 0x1000
	s_addc_u32 s63, s63, 0
	s_add_u32 s64, s64, 0x4000
	s_addc_u32 s65, s65, 0
	s_waitcnt lgkmcnt(0)
	v_mfma_f32_16x16x32_bf16 v[100:103], v[68:71], v[84:87], 0
	v_mfma_f32_16x16x32_bf16 v[100:103], v[72:75], v[88:91], v[100:103]
	v_mfma_f32_16x16x32_bf16 v[100:103], v[76:79], v[92:95], v[100:103]
	v_mfma_f32_16x16x32_bf16 v[100:103], v[80:83], v[96:99], v[100:103]
	s_add_i32 s68, s68, 0x5000
	s_cmp_lg_u32 s68, 0x19000
	s_cselect_b32 s68, s68, 0x5000
	s_nop 7
	v_pk_mul_f32 v[100:101], v[100:101], s[22:23] op_sel_hi:[1,0]
	v_pk_mul_f32 v[102:103], v[102:103], s[22:23] op_sel_hi:[1,0]
	s_cmpk_lt_u32 s54, 0x20
	v_cvt_pk_bf16_f32 v104, v100, v101
	v_cvt_pk_bf16_f32 v105, v102, v103
	s_cbranch_scc0 .Lgla_nost1
	global_store_dwordx2 v2, v[104:105], s[66:67]
.Lgla_nost1:
	s_add_u32 s66, s66, 0x1000
	s_addc_u32 s67, s67, 0
	s_add_i32 s54, s54, 1
	s_waitcnt vmcnt(11)
	s_cmpk_lt_u32 s54, 0x1d
	s_cselect_b64 s[72:73], -1, 0
	s_cmpk_lt_u32 s54, 0x1e
	s_cselect_b64 s[74:75], -1, 0
	v_add_u32_e32 v5, s68, v0
	ds_read_b128 v[52:55], v5
	ds_read_b128 v[56:59], v5 offset:1024
	ds_read_b128 v[60:63], v5 offset:2048
	ds_read_b128 v[64:67], v5 offset:3072
	v_pk_mul_f32 v[8:9], v[8:9], v[48:49]
	v_pk_mul_f32 v[10:11], v[10:11], v[50:51]
	v_pk_mul_f32 v[12:13], v[12:13], v[48:49]
	v_pk_mul_f32 v[14:15], v[14:15], v[50:51]
	s_and_b32 s69, s54, 1
	s_mulk_i32 s69, 0x2200
	v_add_u32_e32 v6, s69, v3
	v_add_u32_e32 v7, s69, v4
	s_waitcnt lgkmcnt(0)
	s_nop 0
	v_mfma_f32_16x16x32_bf16 v[8:11], v[40:43], v[52:55], v[8:11]
	v_mfma_f32_16x16x32_bf16 v[12:15], v[40:43], v[60:63], v[12:15]
	v_mfma_f32_16x16x32_bf16 v[8:11], v[44:47], v[56:59], v[8:11]
	v_mfma_f32_16x16x32_bf16 v[12:15], v[44:47], v[64:67], v[12:15]
	s_mov_b64 exec, s[74:75]
	global_load_dwordx4 v[28:31], v0, s[58:59]
	global_load_dwordx4 v[32:35], v0, s[58:59] offset:1024
	global_load_dwordx4 v[36:39], v1, s[60:61]
	s_add_u32 s58, s58, 0x4000
	s_addc_u32 s59, s59, 0
	s_add_u32 s60, s60, 0x200
	s_addc_u32 s61, s61, 0
	s_mov_b64 exec, -1
	s_nop 7
	v_cvt_pk_bf16_f32 v104, v8, v9
	v_cvt_pk_bf16_f32 v105, v10, v11
	v_cvt_pk_bf16_f32 v106, v12, v13
	v_cvt_pk_bf16_f32 v107, v14, v15
	ds_write_b64 v6, v[104:105]
	ds_write_b64 v6, v[106:107] offset:4352
	s_waitcnt vmcnt(11)
	s_waitcnt lgkmcnt(0)
	s_barrier
	v_add_u32_e32 v5, s68, v108
	ds_read_b128 v[68:71], v7
	ds_read_b128 v[72:75], v7 offset:64
	ds_read_b128 v[76:79], v7 offset:128
	ds_read_b128 v[80:83], v7 offset:192
	ds_read_b128 v[84:87], v5
	ds_read_b128 v[88:91], v5 offset:1024
	ds_read_b128 v[92:95], v5 offset:2048
	ds_read_b128 v[96:99], v5 offset:3072
	s_add_i32 s0, s68, 0xffffb000
	s_cmp_lg_u32 s68, 0x5000
	s_cselect_b32 s0, s0, 0x14000
	s_and_b64 exec, s[36:37], s[72:73]
	s_add_i32 m0, s0, s55
	s_nop 0
	global_load_lds_dwordx4 v109, s[62:63]
	s_mov_b64 exec, s[72:73]
	s_add_i32 m0, s0, s53
	s_nop 0
	global_load_lds_dwordx4 v0, s[64:65]
	global_load_lds_dwordx4 v0, s[64:65] offset:1024
	s_mov_b64 exec, -1
	s_add_u32 s62, s62, 0x1000
	s_addc_u32 s63, s63, 0
	s_add_u32 s64, s64, 0x4000
	s_addc_u32 s65, s65, 0
	s_waitcnt lgkmcnt(0)
	v_mfma_f32_16x16x32_bf16 v[100:103], v[68:71], v[84:87], 0
	v_mfma_f32_16x16x32_bf16 v[100:103], v[72:75], v[88:91], v[100:103]
	v_mfma_f32_16x16x32_bf16 v[100:103], v[76:79], v[92:95], v[100:103]
	v_mfma_f32_16x16x32_bf16 v[100:103], v[80:83], v[96:99], v[100:103]
	s_add_i32 s68, s68, 0x5000
	s_cmp_lg_u32 s68, 0x19000
	s_cselect_b32 s68, s68, 0x5000
	s_nop 7
	v_pk_mul_f32 v[100:101], v[100:101], s[22:23] op_sel_hi:[1,0]
	v_pk_mul_f32 v[102:103], v[102:103], s[22:23] op_sel_hi:[1,0]
	s_cmpk_lt_u32 s54, 0x20
	v_cvt_pk_bf16_f32 v104, v100, v101
	v_cvt_pk_bf16_f32 v105, v102, v103
	s_cbranch_scc0 .Lgla_nost2
	global_store_dwordx2 v2, v[104:105], s[66:67]
